# P1 static KV-copy burst slot = blockIdx & 3 (whole XCDs burst together, two XCDs per unit boundary) instead of (blockIdx>>3)&3 (a quarter of every XCD)
# baseline (speedup 1.0000x reference)
.LBB0_165:
	s_and_b32 s16, s50, 3
	v_writelane_b32 v248, s20, 44
	s_cmp_eq_u32 s16, 0
	s_nop 0
	v_writelane_b32 v248, s21, 45
	s_cselect_b64 s[20:21], -1, 0
	s_cmp_lg_u32 s16, 0
	s_cbranch_scc1 .LBB0_169
	s_ashr_i32 s0, s50, 3
	s_and_b32 s2, s50, 7
	s_load_dwordx16 s[36:51], s[52:53], 0x0
	s_mul_hi_i32 s1, s0, 0x1800000
	s_mul_i32 s0, s0, 0x1800000
	s_mul_i32 s2, s2, 0x240000
	s_add_u32 s0, s0, s2
	s_addc_u32 s1, s1, 0
	v_lshl_or_b32 v2, v0, 4, s0
	v_mov_b32_e32 v3, s1
	s_waitcnt lgkmcnt(0)
	v_lshl_add_u64 v[74:75], s[42:43], 0, v[2:3]
	s_load_dwordx16 s[36:51], s[52:53], 0x40
	s_waitcnt vmcnt(0)
	s_mov_b64 s[6:7], 0
	s_mov_b64 s[12:13], 0x1a000
	s_mov_b64 s[14:15], 0x1c000
	s_waitcnt lgkmcnt(0)
	v_lshl_add_u64 v[76:77], s[50:51], 0, v[2:3]
	v_mov_b32_e32 v2, 0
	s_mov_b64 s[24:25], 0x1e000
	s_mov_b64 s[26:27], 0x20000
	s_mov_b64 s[28:29], 0x22000
	s_mov_b64 s[34:35], 0x24000
	s_mov_b64 s[42:43], 0x26000
	s_mov_b64 s[46:47], 0x28000
	s_mov_b64 s[56:57], 0x2a000
	s_mov_b64 s[58:59], 0x2c000
	s_mov_b64 s[60:61], 0x2e000
	s_mov_b64 s[64:65], 0xa31c000
	s_mov_b64 s[66:67], 0xa31e000
	s_mov_b64 s[68:69], 0xa320000
	s_mov_b64 s[0:1], 0xa322000
	s_mov_b64 s[70:71], 0xa324000
	s_mov_b64 s[72:73], 0xa326000
	s_mov_b64 s[74:75], 0xa328000
	s_mov_b64 s[76:77], 0xa32a000
	v_mov_b32_e32 v3, v2
	v_mov_b32_e32 v4, v2
	v_mov_b32_e32 v5, v2
	v_mov_b32_e32 v6, v2
	v_mov_b32_e32 v7, v2
	v_mov_b32_e32 v8, v2
	v_mov_b32_e32 v9, v2
	v_mov_b32_e32 v10, v2
	v_mov_b32_e32 v11, v2
	v_mov_b32_e32 v12, v2
	v_mov_b32_e32 v13, v2
	v_mov_b32_e32 v14, v2
	v_mov_b32_e32 v15, v2
	v_mov_b32_e32 v16, v2
	v_mov_b32_e32 v17, v2
	v_mov_b32_e32 v18, v2
	v_mov_b32_e32 v19, v2
	v_mov_b32_e32 v20, v2
	v_mov_b32_e32 v21, v2
	v_mov_b32_e32 v22, v2
	v_mov_b32_e32 v23, v2
	v_mov_b32_e32 v24, v2
	v_mov_b32_e32 v25, v2
	v_mov_b32_e32 v26, v2
	v_mov_b32_e32 v27, v2
	v_mov_b32_e32 v28, v2
	v_mov_b32_e32 v29, v2
	v_mov_b32_e32 v30, v2
	v_mov_b32_e32 v31, v2
	v_mov_b32_e32 v32, v2
	v_mov_b32_e32 v33, v2
	v_mov_b32_e32 v34, v2
	v_mov_b32_e32 v35, v2
	v_mov_b32_e32 v36, v2
	v_mov_b32_e32 v37, v2
	v_mov_b32_e32 v38, v2
	v_mov_b32_e32 v39, v2
	v_mov_b32_e32 v40, v2
	v_mov_b32_e32 v41, v2
	v_mov_b32_e32 v42, v2
	v_mov_b32_e32 v43, v2
	v_mov_b32_e32 v44, v2
	v_mov_b32_e32 v45, v2
	v_mov_b32_e32 v46, v2
	v_mov_b32_e32 v47, v2
	v_mov_b32_e32 v48, v2
	v_mov_b32_e32 v49, v2
	v_mov_b32_e32 v50, v2
	v_mov_b32_e32 v51, v2
	v_mov_b32_e32 v52, v2
	v_mov_b32_e32 v53, v2
	v_mov_b32_e32 v54, v2
	v_mov_b32_e32 v55, v2
	v_mov_b32_e32 v56, v2
	v_mov_b32_e32 v57, v2
	v_mov_b32_e32 v58, v2
	v_mov_b32_e32 v59, v2
	v_mov_b32_e32 v60, v2
	v_mov_b32_e32 v61, v2
	v_mov_b32_e32 v62, v2
	v_mov_b32_e32 v63, v2
	v_mov_b32_e32 v64, v2
	v_mov_b32_e32 v65, v2
	v_mov_b32_e32 v66, v2
	v_mov_b32_e32 v67, v2
	v_mov_b32_e32 v68, v2
	v_mov_b32_e32 v69, v2
	v_mov_b32_e32 v70, v2
	v_mov_b32_e32 v71, v2
	v_mov_b32_e32 v72, v2
	v_mov_b32_e32 v73, v2
	s_mov_b64 s[78:79], 0xa32c000
	s_mov_b64 s[80:81], 0xa32e000
	s_mov_b64 s[82:83], 0xa330000
	s_mov_b64 s[84:85], 0xa332000
	s_mov_b64 s[86:87], 0xa334000
	s_mov_b64 s[88:89], 0xa336000
	s_mov_b64 s[90:91], 0xa338000
	s_mov_b64 s[92:93], 0xa33a000
	s_mov_b64 s[94:95], 0xa33c000
	s_mov_b64 s[96:97], 0xa33e000
